# p_convert: wait for the next tile's loads moved from loop top to just before the following tile's loads are issued (loads now overlap pack, barrier and tile bookkeeping); preheader wait added
# speedup vs baseline: 1.0138x; 1.0047x over previous
; #define LAS __attribute__((address_space(3)))
; DI void p_convert(const Frame& F) {
;     LAS unsigned* ts = (LAS unsigned*)F.lds;
;     int t = F.vcu; CvTile cur = cv_tile(F, t), nx1 = cv_tile(F, t + F.G); f32x4 r0[4], r1[4]; int buf = 0;
;     if (cur.ok) cv_load(F, cur, r0);
;     if (nx1.ok) cv_load(F, nx1, r1);
;     while (cur.ok) {
.LBB0_271:
	s_and_b64 vcc, exec, s[4:5]
	s_cbranch_vccnz .LBB0_342
	v_ashrrev_i32_e32 v0, 4, v130
	s_movk_i32 s4, 0x104
	v_mul_lo_u32 v3, v0, s4
	s_lshl_b32 s4, s64, 1
	v_readlane_b32 s12, v254, 55
	v_readlane_b32 s13, v254, 56
	s_add_u32 s38, s12, 0x3500000
	s_addc_u32 s39, s13, 0
	s_add_u32 s52, s12, 0x2500000
	s_addc_u32 s53, s13, 0
	s_add_u32 s57, s12, 0x1d00000
	s_addc_u32 s58, s13, 0
	v_lshlrev_b32_e32 v0, 2, v130
	s_add_u32 s59, s12, 0x1a00000
	v_and_b32_e32 v2, 60, v0
	s_addc_u32 s60, s13, 0
	v_and_b32_e32 v0, 7, v130
	s_add_u32 s61, s12, 0x8d00000
	v_ashrrev_i32_e32 v10, 3, v130
	v_mul_u32_u24_e32 v13, 0x410, v0
	v_lshlrev_b32_e32 v0, 3, v0
	s_addc_u32 s62, s13, 0
	v_and_b32_e32 v11, -2, v10
	v_or_b32_e32 v12, 1, v10
	s_add_i32 s63, s69, s4
	s_mov_b32 s71, 0
	v_lshlrev_b32_e32 v4, 1, v0
	s_waitcnt vmcnt(0)
	s_mov_b32 s100, 0
	v_mov_b32_e32 v184, 1.0
	v_mov_b32_e32 v186, 1.0
	v_mov_b32_e32 v188, 1.0
	v_mov_b32_e32 v190, 1.0
	s_branch .LBB0_274

; #define LAS __attribute__((address_space(3)))
; DI unsigned pk2(float a, float b) { f32x2 v = {a, b}; bfv2 r = __builtin_convertvector(v, bfv2); return __builtin_bit_cast(unsigned, r); }
; DI CvTile cv_tile(const Frame& F, int t) {
;     CvTile r; r.ok = false;
;     constexpr int NTN[6] = {26, 12, 16, 16, 88, 16}, NT_[6] = {26 * 32, 12 * 8, 16 * 8, 16 * 32, 88 * 32, 16 * 88};
;     constexpr int PER_LAYER = NT_[0] + NT_[1] + NT_[2] + NT_[3] + NT_[4] + NT_[5];
;     if (t >= 2 * PER_LAYER) return r;
;     const int l = t >= PER_LAYER ? 1 : 0; t -= l * PER_LAYER;
;     int j = 0, nt = 0, kt = 0;
; #pragma unroll
;     for (int q = 0; q < 6; ++q) { if (t >= 0 && t < NT_[q]) { j = q; nt = t % NTN[q]; kt = t / NTN[q]; } t -= NT_[q]; }
; DI void p_convert(const Frame& F) {
;     ...
;     while (cur.ok) {
;         LAS unsigned* tb = ts + buf * (2 * 32 * 65);
; #pragma unroll
;         for (int h = 0; h < 2; ++h) { LAS unsigned* q = tb + h * (32 * 65) + (F.tid >> 4) * 65 + (F.tid & 15) * 4;
; #pragma unroll
;             for (int i = 0; i < 4; ++i) q[i] = pk2(r0[h * 2][i], r0[h * 2 + 1][i]); }
;         __syncthreads();
; #pragma unroll
;         for (int i = 0; i < 4; ++i) r0[i] = r1[i];
;         const CvTile nx2 = cv_tile(F, t + 2 * F.G);
.LBB0_274:
	v_mov_b64_e32 v[62:63], v[30:31]
	s_mul_i32 s4, s71, 0x4100
	v_mov_b64_e32 v[52:53], v[20:21]
	v_mov_b64_e32 v[48:49], v[16:17]
	s_add_i32 s69, s4, 0
	v_lshlrev_b32_e32 v0, 2, v2
	v_mov_b64_e32 v[54:55], v[22:23]
	v_mov_b64_e32 v[50:51], v[18:19]
	v_add3_u32 v5, s69, v3, v0
	v_cvt_pk_bf16_f32 v6, v48, v52
	v_cvt_pk_bf16_f32 v7, v49, v53
	v_mov_b64_e32 v[60:61], v[28:29]
	v_mov_b64_e32 v[56:57], v[24:25]
	ds_write2_b32 v5, v6, v7 offset1:1
	v_cvt_pk_bf16_f32 v6, v50, v54
	v_cvt_pk_bf16_f32 v7, v51, v55
	v_mov_b64_e32 v[58:59], v[26:27]
	ds_write2_b32 v5, v6, v7 offset0:2 offset1:3
	v_add_u32_e32 v6, 0x2080, v5
	v_cvt_pk_bf16_f32 v7, v56, v60
	v_cvt_pk_bf16_f32 v8, v57, v61
	s_cmpk_lt_i32 s63, 0x2d40
	ds_write2_b32 v6, v7, v8 offset1:1
	v_cvt_pk_bf16_f32 v6, v58, v62
	v_add_u32_e32 v5, 0x2088, v5
	v_cvt_pk_bf16_f32 v7, v59, v63
	s_cselect_b64 s[4:5], -1, 0
	s_cmpk_gt_i32 s63, 0x2d3f
	ds_write2_b32 v5, v6, v7 offset1:1
	s_waitcnt lgkmcnt(0)
	s_barrier
	s_cbranch_scc1 .LBB0_319
	s_cmpk_gt_i32 s63, 0x169f
	s_cselect_b64 s[12:13], -1, 0
	s_and_b64 s[14:15], s[12:13], exec
	s_cselect_b32 s91, 0xffffe960, 0
	s_add_i32 s91, s91, s63
	s_mov_b32 s7, 0
	s_cmpk_lt_u32 s91, 0x340
	s_mov_b32 s15, 0
	s_mov_b32 s14, 0
	s_cbranch_scc0 .LBB0_277
	s_and_b32 s14, s91, 0xffff
	s_mulk_i32 s14, 0x4ec5
	s_lshr_b32 s14, s14, 19
	s_mul_i32 s15, s14, 26
	s_sub_i32 s15, s91, s15
	s_and_b32 s15, s15, 0xffff

; DI void p_convert(const Frame& F) {
;     ...
; #pragma unroll
;         for (int i = 0; i < 4; ++i) r0[i] = r1[i];
;         const CvTile nx2 = cv_tile(F, t + 2 * F.G);
;         if (nx2.ok) cv_load(F, nx2, r1);
.LBB0_318:
	s_lshl_b32 s34, s34, 6
.LBB0_319:
	s_waitcnt vmcnt(0)
	s_cmp_eq_u32 s100, 0
	s_cbranch_scc1 .Lcv_nomul
	v_pk_mul_f32 v[34:35], v[34:35], v[184:185] op_sel_hi:[1,0]
	v_pk_mul_f32 v[32:33], v[32:33], v[184:185] op_sel_hi:[1,0]
	v_pk_mul_f32 v[38:39], v[38:39], v[186:187] op_sel_hi:[1,0]
	v_pk_mul_f32 v[36:37], v[36:37], v[186:187] op_sel_hi:[1,0]
	v_pk_mul_f32 v[42:43], v[42:43], v[188:189] op_sel_hi:[1,0]
	v_pk_mul_f32 v[40:41], v[40:41], v[188:189] op_sel_hi:[1,0]
	v_pk_mul_f32 v[46:47], v[46:47], v[190:191] op_sel_hi:[1,0]
	v_pk_mul_f32 v[44:45], v[44:45], v[190:191] op_sel_hi:[1,0]
	s_mov_b32 s100, 0
.Lcv_nomul:
	v_mov_b32_e32 v184, 1.0
	v_mov_b32_e32 v186, 1.0
	v_mov_b32_e32 v188, 1.0
	v_mov_b32_e32 v190, 1.0
	v_mov_b64_e32 v[16:17], v[32:33]
	v_mov_b64_e32 v[18:19], v[34:35]
	v_mov_b64_e32 v[20:21], v[36:37]
	v_mov_b64_e32 v[22:23], v[38:39]
	v_mov_b64_e32 v[24:25], v[40:41]
	v_mov_b64_e32 v[26:27], v[42:43]
	v_mov_b64_e32 v[28:29], v[44:45]
	v_mov_b64_e32 v[30:31], v[46:47]
	v_mov_b64_e32 v[46:47], v[30:31]
	s_xor_b64 s[10:11], s[10:11], -1
	s_andn2_b64 vcc, exec, s[4:5]
	v_mov_b64_e32 v[44:45], v[28:29]
	v_mov_b64_e32 v[42:43], v[26:27]
	v_mov_b64_e32 v[40:41], v[24:25]
	v_mov_b64_e32 v[38:39], v[22:23]
	v_mov_b64_e32 v[36:37], v[20:21]
	v_mov_b64_e32 v[34:35], v[18:19]
	v_mov_b64_e32 v[32:33], v[16:17]
	s_cbranch_vccnz .LBB0_273
	s_cmp_lt_i32 s22, 0
	s_mov_b64 s[42:43], -1
	s_cbranch_scc0 .LBB0_322
	s_mov_b64 s[42:43], 0
